# split grid barriers: normM->w_in and post->q become group barriers; grid-wide conditions (ACT reads done / post rows written) as arrive counters + late waits in front of the first MIX store and the kv
# speedup vs baseline: 1.0062x; 1.0062x over previous
.LBB0_284:
	v_readlane_b32 s4, v255, 15
	s_add_i32 s34, s4, 1
	v_readlane_b32 s4, v255, 0
	v_readlane_b32 s5, v255, 1
	s_cmp_ge_i32 s34, s5
	s_cbranch_scc1 .LBB0_338
	s_bitcmp0_b32 s32, 0
	s_cbranch_scc1 .Lgb0_slow
	s_waitcnt vmcnt(0)
	s_barrier
	s_add_i32 s32, s32, 16
	v_cmp_eq_u32_e32 vcc, 0, v0
	s_and_saveexec_b64 s[4:5], vcc
	s_cbranch_execz .Lgb0_join
	s_load_dwordx2 s[8:9], s[0:1], 0xd8
	s_and_b32 s11, s87, 63
	s_lshl_b32 s11, s11, 8
	v_mov_b32_e32 v248, 0
	v_mov_b32_e32 v249, 1
	s_mov_b32 s10, 0
	s_waitcnt lgkmcnt(0)
	s_add_u32 s8, s8, 0x10000
	s_addc_u32 s9, s9, 0
	s_add_u32 s8, s8, s11
	s_addc_u32 s9, s9, 0
	global_atomic_add v248, v249, s[8:9]
	buffer_inv sc1
.Lgb0_spin:
	global_load_dword v250, v248, s[8:9] sc1
	s_waitcnt vmcnt(0)
	v_readfirstlane_b32 s11, v250
	s_nop 3
	s_lshl_b32 s11, s11, 2
	s_or_b32 s11, s11, 15
	s_cmp_ge_u32 s11, s32
	s_cbranch_scc1 .Lgb0_done
	s_add_i32 s10, s10, 1
	s_cmp_gt_u32 s10, 0x8000
	s_cbranch_scc1 .Lgb0_done
	s_sleep 1
	s_branch .Lgb0_spin

.LBB0_359:
	v_readlane_b32 s4, v255, 15
	s_add_i32 s34, s4, 2
	v_readlane_b32 s4, v255, 0
	v_readlane_b32 s5, v255, 1
	s_cmp_ge_i32 s34, s5
	s_cbranch_scc1 .LBB0_413
	s_bitcmp0_b32 s32, 0
	s_cbranch_scc1 .Lgb1_slow
	s_waitcnt vmcnt(0)
	s_barrier
	s_add_i32 s32, s32, 16
	v_cmp_eq_u32_e32 vcc, 0, v0
	s_and_saveexec_b64 s[4:5], vcc
	s_cbranch_execz .Lgb1_join
	s_load_dwordx2 s[8:9], s[0:1], 0xd8
	s_and_b32 s11, s87, 63
	s_lshl_b32 s11, s11, 8
	v_mov_b32_e32 v248, 0
	v_mov_b32_e32 v249, 1
	s_mov_b32 s10, 0
	s_waitcnt lgkmcnt(0)
	s_add_u32 s8, s8, 0x10000
	s_addc_u32 s9, s9, 0
	s_add_u32 s8, s8, s11
	s_addc_u32 s9, s9, 0
	global_atomic_add v248, v249, s[8:9]
	buffer_inv sc1

.LBB0_442:
	v_readlane_b32 s4, v255, 15
	s_add_i32 s34, s4, 3
	v_readlane_b32 s4, v255, 0
	v_readlane_b32 s5, v255, 1
	s_cmp_ge_i32 s34, s5
	s_cbranch_scc1 .LBB0_496
	s_bitcmp0_b32 s32, 0
	s_cbranch_scc1 .Lgb2_slow
	s_cmp_eq_u32 s34, 25
	s_cbranch_scc1 .Lgb2_slow
	s_waitcnt vmcnt(0)
	s_barrier
	s_add_i32 s32, s32, 16
	v_cmp_eq_u32_e32 vcc, 0, v0
	s_and_saveexec_b64 s[4:5], vcc
	s_cbranch_execz .Lgb2_join
	s_load_dwordx2 s[8:9], s[0:1], 0xd8
	s_and_b32 s11, s87, 63
	s_lshl_b32 s11, s11, 8
	v_mov_b32_e32 v248, 0
	v_mov_b32_e32 v249, 1
	s_mov_b32 s10, 0
	s_waitcnt lgkmcnt(0)
	s_add_u32 s8, s8, 0x10000
	s_addc_u32 s9, s9, 0
	s_bitcmp1_b32 s34, 0
	s_cbranch_scc1 .Lgb2_noarr
	global_atomic_add v248, v249, s[8:9] offset:128
.Lgb2_noarr:
	s_add_u32 s8, s8, s11
	s_addc_u32 s9, s9, 0
	global_atomic_add v248, v249, s[8:9]
	buffer_inv sc1

.LBB0_507:
	s_or_b64 exec, exec, s[6:7]
	v_readlane_b32 s4, v255, 15
	s_add_i32 s17, s4, 4
	v_readlane_b32 s4, v255, 0
	v_readlane_b32 s5, v255, 1
	s_cmp_ge_i32 s17, s5
	s_cbranch_scc1 .LBB0_562
	s_bitcmp0_b32 s32, 0
	s_cbranch_scc1 .Lgb5_slow
	s_load_dwordx2 s[8:9], s[0:1], 0xd8
	v_mov_b32_e32 v248, 0
	s_waitcnt lgkmcnt(0)
	s_add_u32 s8, s8, 0x10000
	s_addc_u32 s9, s9, 0
	global_load_dword v251, v248, s[8:9] offset:128 sc1
	s_waitcnt vmcnt(0)
	s_barrier
	s_add_i32 s32, s32, 16
	v_readfirstlane_b32 s10, v251
	v_readlane_b32 s11, v255, 15
	s_cmp_gt_u32 s11, 6
	s_cselect_b32 s11, 2, 1
	s_lshl_b32 s11, s11, 8
	s_cmp_ge_u32 s10, s11
	s_cbranch_scc1 .Lgb5_np
	s_or_b32 s32, s32, 2
.Lgb5_np:
	v_cmp_eq_u32_e32 vcc, 0, v0
	s_and_saveexec_b64 s[4:5], vcc
	s_cbranch_execz .Lgb5_join
	s_load_dwordx2 s[8:9], s[0:1], 0xd8
	s_and_b32 s11, s87, 63
	s_lshl_b32 s11, s11, 8
	v_mov_b32_e32 v248, 0
	v_mov_b32_e32 v249, 1
	s_mov_b32 s10, 0
	s_waitcnt lgkmcnt(0)
	s_add_u32 s8, s8, 0x10000
	s_addc_u32 s9, s9, 0
	s_add_u32 s8, s8, s11
	s_addc_u32 s9, s9, 0
	global_atomic_add v248, v249, s[8:9]
	buffer_inv sc1

.Lgb5_slow:
	s_mov_b64 s[6:7], s[0:1]
	s_mov_b32 s34, s90
	s_waitcnt vmcnt(0)
	s_waitcnt vmcnt(0)
	s_barrier
	s_mov_b64 s[4:5], exec
	v_readlane_b32 s8, v255, 5
	v_readlane_b32 s9, v255, 6
	s_and_b64 s[8:9], s[4:5], s[8:9]
	s_mov_b64 exec, s[8:9]
	s_cbranch_execz .LBB0_561
	v_readlane_b32 s8, v255, 16
	s_load_dwordx2 s[6:7], s[6:7], 0xd8
	s_waitcnt vmcnt(0) expcnt(0) lgkmcnt(0)
	v_mov_b32_e32 v2, s8
	ds_read_b32 v5, v2
	v_readlane_b32 s8, v255, 17
	s_waitcnt lgkmcnt(0)
	v_cmp_ne_u32_e32 vcc, 0, v5
	v_mov_b32_e32 v2, s8
	ds_read_b32 v4, v2
	s_cbranch_vccnz .LBB0_525
	v_readlane_b32 s8, v255, 2
	v_readlane_b32 s9, v255, 3
	s_load_dwordx2 s[14:15], s[8:9], 0x4
	s_add_u32 s8, s6, 0x4200
	s_addc_u32 s9, s7, 0
	s_add_u32 s10, s6, 0x4400
	s_addc_u32 s11, s7, 0
	s_waitcnt lgkmcnt(0)
	s_mul_i32 s35, s14, s65
	s_add_u32 s14, s6, 0x4500
	s_mul_i32 s35, s35, s15
	s_addc_u32 s15, s7, 0
	s_add_u32 s18, s6, 0x4600
	s_addc_u32 s19, s7, 0
	s_add_u32 s20, s6, 0x4700
	s_addc_u32 s21, s7, 0
	s_add_u32 s22, s6, 0x4800
	s_addc_u32 s23, s7, 0
	s_add_u32 s24, s6, 0x4900
	s_addc_u32 s25, s7, 0
	s_add_u32 s26, s6, 0x4a00
	s_addc_u32 s27, s7, 0
	s_add_u32 s28, s6, 0x4b00
	s_addc_u32 s29, s7, 0
	s_add_u32 s30, s6, 0x4c00
	s_addc_u32 s31, s7, 0
	s_add_u32 s36, s6, 0x4d00
	s_addc_u32 s37, s7, 0
	s_add_u32 s44, s6, 0x4e00
	s_addc_u32 s45, s7, 0
	s_add_u32 s46, s6, 0x4f00
	s_addc_u32 s47, s7, 0
	s_add_u32 s72, s6, 0x5000
	s_addc_u32 s73, s7, 0
	s_add_u32 s74, s6, 0x5100
	s_addc_u32 s75, s7, 0
	s_add_u32 s76, s6, 0x5200
	s_addc_u32 s77, s7, 0
	s_add_u32 s78, s6, 0x5300
	s_addc_u32 s79, s7, 0
	s_mov_b32 s40, 1
	s_branch .LBB0_512

.LBB0_581:
	s_bitcmp1_b32 s32, 1
	s_cbranch_scc0 .Lgw1_skip
	s_load_dwordx2 s[78:79], s[0:1], 0xd8
	v_mov_b32_e32 v248, 0
	s_waitcnt lgkmcnt(0)
	s_add_u32 s78, s78, 0x10000
	s_addc_u32 s79, s79, 0
	v_readlane_b32 s96, v255, 15
	s_cmp_gt_u32 s96, 6
	s_cselect_b32 s96, 2, 1
	s_lshl_b32 s96, s96, 8
	s_mov_b32 s97, 0
.Lgw1_spin:
	global_load_dword v250, v248, s[78:79] offset:128 sc1
	s_waitcnt vmcnt(0)
	v_readfirstlane_b32 s36, v250
	s_nop 3
	s_cmp_ge_u32 s36, s96
	s_cbranch_scc1 .Lgw1_done
	s_add_i32 s97, s97, 1
	s_cmp_gt_u32 s97, 0x8000
	s_cbranch_scc1 .Lgw1_done
	s_sleep 1
	s_branch .Lgw1_spin
.Lgw1_done:
	s_bitset0_b32 s32, 1

.LBB0_725:
	v_readlane_b32 s4, v255, 15
	s_add_i32 s17, s4, 5
	v_readlane_b32 s4, v255, 0
	v_readlane_b32 s5, v255, 1
	s_cmp_ge_i32 s17, s5
	s_waitcnt vmcnt(0)
	s_barrier
	s_cbranch_scc1 .LBB0_779
	s_bitcmp0_b32 s32, 0
	s_cbranch_scc1 .Lgb4_slow
	s_waitcnt vmcnt(0)
	s_barrier
	s_add_i32 s32, s32, 16
	v_cmp_eq_u32_e32 vcc, 0, v0
	s_and_saveexec_b64 s[4:5], vcc
	s_cbranch_execz .Lgb4_join
	s_load_dwordx2 s[8:9], s[0:1], 0xd8
	s_and_b32 s11, s87, 63
	s_lshl_b32 s11, s11, 8
	v_mov_b32_e32 v248, 0
	v_mov_b32_e32 v249, 1
	s_mov_b32 s10, 0
	s_waitcnt lgkmcnt(0)
	s_add_u32 s8, s8, 0x10000
	s_addc_u32 s9, s9, 0
	s_add_u32 s8, s8, s11
	s_addc_u32 s9, s9, 0
	global_atomic_add v248, v249, s[8:9]
	buffer_inv sc1

.LBB0_813:
	s_or_b64 exec, exec, s[6:7]
	v_readlane_b32 s4, v255, 15
	s_add_i32 s17, s4, 6
	v_readlane_b32 s4, v255, 0
	v_readlane_b32 s5, v255, 1
	s_cmp_ge_i32 s17, s5
	s_cbranch_scc1 .LBB0_867
	s_bitcmp0_b32 s32, 0
	s_cbranch_scc1 .Lgb6_slow
	s_waitcnt vmcnt(0)
	s_barrier
	s_add_i32 s32, s32, 16
	s_or_b32 s32, s32, 4
	v_cmp_eq_u32_e32 vcc, 0, v0
	s_and_saveexec_b64 s[4:5], vcc
	s_cbranch_execz .Lgb6_join
	s_load_dwordx2 s[8:9], s[0:1], 0xd8
	s_and_b32 s11, s87, 63
	s_lshl_b32 s11, s11, 8
	v_mov_b32_e32 v248, 0
	v_mov_b32_e32 v249, 1
	s_mov_b32 s10, 0
	s_waitcnt lgkmcnt(0)
	s_add_u32 s8, s8, 0x10000
	s_addc_u32 s9, s9, 0
	buffer_wbl2 sc1
	s_waitcnt vmcnt(0)
	global_atomic_add v248, v249, s[8:9] offset:384
	s_add_u32 s8, s8, s11
	s_addc_u32 s9, s9, 0
	global_atomic_add v248, v249, s[8:9]
	buffer_inv sc1

.Lgb6_slow:
	s_mov_b64 s[6:7], s[0:1]
	s_mov_b32 s34, s90
	s_waitcnt vmcnt(0)
	s_waitcnt vmcnt(0) lgkmcnt(0)
	s_barrier
	s_mov_b64 s[4:5], exec
	v_readlane_b32 s8, v255, 5
	v_readlane_b32 s9, v255, 6
	s_and_b64 s[8:9], s[4:5], s[8:9]
	s_mov_b64 exec, s[8:9]
	s_cbranch_execz .LBB0_866
	v_readlane_b32 s8, v255, 16
	s_load_dwordx2 s[6:7], s[6:7], 0xd8
	s_waitcnt vmcnt(0) expcnt(0) lgkmcnt(0)
	v_mov_b32_e32 v2, s8
	ds_read_b32 v5, v2
	v_readlane_b32 s8, v255, 17
	s_waitcnt lgkmcnt(0)
	v_cmp_ne_u32_e32 vcc, 0, v5
	v_mov_b32_e32 v2, s8
	ds_read_b32 v4, v2
	s_cbranch_vccnz .LBB0_830
	v_readlane_b32 s8, v255, 2
	v_readlane_b32 s9, v255, 3
	s_load_dwordx2 s[14:15], s[8:9], 0x4
	s_add_u32 s8, s6, 0x4200
	s_addc_u32 s9, s7, 0
	s_add_u32 s10, s6, 0x4400
	s_addc_u32 s11, s7, 0
	s_waitcnt lgkmcnt(0)
	s_mul_i32 s35, s14, s65
	s_add_u32 s14, s6, 0x4500
	s_mul_i32 s35, s35, s15
	s_addc_u32 s15, s7, 0
	s_add_u32 s18, s6, 0x4600
	s_addc_u32 s19, s7, 0
	s_add_u32 s20, s6, 0x4700
	s_addc_u32 s21, s7, 0
	s_add_u32 s22, s6, 0x4800
	s_addc_u32 s23, s7, 0
	s_add_u32 s24, s6, 0x4900
	s_addc_u32 s25, s7, 0
	s_add_u32 s26, s6, 0x4a00
	s_addc_u32 s27, s7, 0
	s_add_u32 s28, s6, 0x4b00
	s_addc_u32 s29, s7, 0
	s_add_u32 s30, s6, 0x4c00
	s_addc_u32 s31, s7, 0
	s_add_u32 s36, s6, 0x4d00
	s_addc_u32 s37, s7, 0
	s_add_u32 s44, s6, 0x4e00
	s_addc_u32 s45, s7, 0
	s_add_u32 s46, s6, 0x4f00
	s_addc_u32 s47, s7, 0
	s_add_u32 s72, s6, 0x5000
	s_addc_u32 s73, s7, 0
	s_add_u32 s74, s6, 0x5100
	s_addc_u32 s75, s7, 0
	s_add_u32 s76, s6, 0x5200
	s_addc_u32 s77, s7, 0
	s_add_u32 s78, s6, 0x5300
	s_addc_u32 s79, s7, 0
	s_mov_b32 s40, 1
	s_branch .LBB0_818

.LBB0_925:
	s_bitcmp1_b32 s32, 2
	s_cbranch_scc0 .Lgw2_a
	s_load_dwordx2 s[8:9], s[0:1], 0xd8
	v_mov_b32_e32 v248, 0
	s_waitcnt lgkmcnt(0)
	s_add_u32 s8, s8, 0x10000
	s_addc_u32 s9, s9, 0
	global_load_dword v251, v248, s[8:9] offset:384 sc1
.Lgw2_a:
	s_waitcnt vmcnt(0)
	v_readlane_b32 s87, v255, 19
	v_readlane_b32 s66, v255, 48
	s_barrier
	v_readlane_b32 s67, v255, 49
	s_bitcmp1_b32 s32, 2
	s_cbranch_scc0 .Lgw2_b
	v_readfirstlane_b32 s10, v251
	v_readlane_b32 s11, v255, 15
	s_cmp_gt_u32 s11, 6
	s_cselect_b32 s11, 2, 1
	s_lshl_b32 s11, s11, 8
	s_cmp_ge_u32 s10, s11
	s_cbranch_scc0 .Lgw2_b
	buffer_inv sc1
	s_bitset0_b32 s32, 2
.Lgw2_b:
.LBB0_926:
	s_bitcmp1_b32 s32, 2
	s_cbranch_scc0 .Lgw2_skip
	s_load_dwordx2 s[8:9], s[0:1], 0xd8
	v_mov_b32_e32 v248, 0
	s_waitcnt lgkmcnt(0)
	s_add_u32 s8, s8, 0x10000
	s_addc_u32 s9, s9, 0
	v_readlane_b32 s11, v255, 15
	s_cmp_gt_u32 s11, 6
	s_cselect_b32 s11, 2, 1
	s_lshl_b32 s11, s11, 8
	s_mov_b32 s10, 0
.Lgw2_spin:
	global_load_dword v250, v248, s[8:9] offset:384 sc1
	s_waitcnt vmcnt(0)
	v_readfirstlane_b32 s4, v250
	s_nop 3
	s_cmp_ge_u32 s4, s11
	s_cbranch_scc1 .Lgw2_done
	s_add_i32 s10, s10, 1
	s_cmp_gt_u32 s10, 0x8000
	s_cbranch_scc1 .Lgw2_done
	s_sleep 1
	s_branch .Lgw2_spin
.Lgw2_done:
	buffer_inv sc1
	s_bitset0_b32 s32, 2

.LBB0_1221:
	s_bitcmp0_b32 s32, 0
	s_cbranch_scc1 .Lgb3_slow
	s_waitcnt vmcnt(0)
	s_barrier
	s_add_i32 s32, s32, 16
	v_cmp_eq_u32_e32 vcc, 0, v0
	s_and_saveexec_b64 s[4:5], vcc
	s_cbranch_execz .Lgb3_join
	s_load_dwordx2 s[8:9], s[0:1], 0xd8
	s_and_b32 s11, s87, 63
	s_lshl_b32 s11, s11, 8
	v_mov_b32_e32 v248, 0
	v_mov_b32_e32 v249, 1
	s_mov_b32 s10, 0
	s_waitcnt lgkmcnt(0)
	s_add_u32 s8, s8, 0x10000
	s_addc_u32 s9, s9, 0
	s_add_u32 s8, s8, s11
	s_addc_u32 s9, s9, 0
	global_atomic_add v248, v249, s[8:9]
	buffer_inv sc1
